# peel with strict waits: C=0 first-touch MFMAs only (no acc zeroing for non-first units)
# baseline (speedup 1.0000x reference)
.Lpeel_108:
	s_add_u32 s0, s40, 0xfffc0080
	s_addc_u32 s1, s41, -1
	s_add_i32 s68, 0, 0x10000
	s_cmp_eq_u32 s47, 12
	s_cselect_b32 s5, s6, s1
	s_cselect_b32 s4, s7, s0
	s_cselect_b32 s1, s37, s46
	s_cselect_b32 s0, s42, s43
	s_add_i32 s70, 0, 0x14000
	v_add_u32_e32 v60, s68, v250
	v_add_u32_e32 v124, s70, v250
	ds_read_b128 v[40:43], v60
	ds_read_b128 v[44:47], v60 offset:1024
	ds_read_b128 v[56:59], v60 offset:2048
	ds_read_b128 v[60:63], v60 offset:3072
	ds_read_b128 v[104:107], v124
	ds_read_b128 v[112:115], v124 offset:1024
	ds_read_b128 v[120:123], v124 offset:2048
	ds_read_b128 v[124:127], v124 offset:3072
	s_add_i32 m0, s20, 0xc000
	ds_read_b128 v[152:155], v251
	ds_read_b128 v[156:159], v251 offset:1024
	ds_read_b128 v[168:171], v251 offset:2048
	ds_read_b128 v[172:175], v251 offset:3072
	ds_read_b128 v[200:203], v251 offset:4096
	ds_read_b128 v[204:207], v251 offset:5120
	ds_read_b128 v[208:211], v251 offset:6144
	ds_read_b128 v[212:215], v251 offset:7168
	global_load_lds_dwordx4 v196, s[40:41]
	s_add_i32 m0, s20, 0xe000
	s_nop 0
	global_load_lds_dwordx4 v198, s[40:41]
	s_waitcnt vmcnt(8)
	s_waitcnt lgkmcnt(0)
	s_barrier
	s_setprio 1
	s_waitcnt lgkmcnt(0)
	v_mfma_f32_16x16x32_bf16 v[164:167], v[40:43], v[152:155], 0
	v_mfma_f32_16x16x32_bf16 v[160:163], v[56:59], v[152:155], 0
	v_mfma_f32_16x16x32_bf16 v[116:119], v[40:43], v[168:171], 0
	v_mfma_f32_16x16x32_bf16 v[108:111], v[56:59], v[168:171], 0
	v_mfma_f32_16x16x32_bf16 v[140:143], v[40:43], v[200:203], 0
	v_mfma_f32_16x16x32_bf16 v[136:139], v[56:59], v[200:203], 0
	v_mfma_f32_16x16x32_bf16 v[92:95], v[40:43], v[208:211], 0
	v_mfma_f32_16x16x32_bf16 v[88:91], v[56:59], v[208:211], 0
	v_mfma_f32_16x16x32_bf16 v[164:167], v[44:47], v[156:159], v[164:167]
	v_mfma_f32_16x16x32_bf16 v[160:163], v[60:63], v[156:159], v[160:163]
	v_mfma_f32_16x16x32_bf16 v[116:119], v[44:47], v[172:175], v[116:119]
	v_mfma_f32_16x16x32_bf16 v[108:111], v[60:63], v[172:175], v[108:111]
	v_mfma_f32_16x16x32_bf16 v[140:143], v[44:47], v[204:207], v[140:143]
	v_mfma_f32_16x16x32_bf16 v[136:139], v[60:63], v[204:207], v[136:139]
	v_mfma_f32_16x16x32_bf16 v[92:95], v[44:47], v[212:215], v[92:95]
	v_mfma_f32_16x16x32_bf16 v[88:91], v[60:63], v[212:215], v[88:91]
	s_setprio 0
	s_setprio 1
	v_mfma_f32_16x16x32_bf16 v[148:151], v[104:107], v[152:155], 0
	v_mfma_f32_16x16x32_bf16 v[144:147], v[120:123], v[152:155], 0
	v_mfma_f32_16x16x32_bf16 v[100:103], v[104:107], v[168:171], 0
	v_mfma_f32_16x16x32_bf16 v[96:99], v[120:123], v[168:171], 0
	v_mfma_f32_16x16x32_bf16 v[132:135], v[104:107], v[200:203], 0
	v_mfma_f32_16x16x32_bf16 v[128:131], v[120:123], v[200:203], 0
	v_mfma_f32_16x16x32_bf16 v[84:87], v[104:107], v[208:211], 0
	v_mfma_f32_16x16x32_bf16 v[80:83], v[120:123], v[208:211], 0
	v_mfma_f32_16x16x32_bf16 v[148:151], v[112:115], v[156:159], v[148:151]
	v_mfma_f32_16x16x32_bf16 v[144:147], v[124:127], v[156:159], v[144:147]
	v_mfma_f32_16x16x32_bf16 v[100:103], v[112:115], v[172:175], v[100:103]
	v_mfma_f32_16x16x32_bf16 v[96:99], v[124:127], v[172:175], v[96:99]
	v_mfma_f32_16x16x32_bf16 v[132:135], v[112:115], v[204:207], v[132:135]
	v_mfma_f32_16x16x32_bf16 v[128:131], v[124:127], v[204:207], v[128:131]
	v_mfma_f32_16x16x32_bf16 v[84:87], v[112:115], v[212:215], v[84:87]
	v_mfma_f32_16x16x32_bf16 v[80:83], v[124:127], v[212:215], v[80:83]
	s_setprio 0
	s_barrier
	s_add_i32 s68, s68, s27
	v_lshl_add_u64 v[178:179], s[0:1], 0, v[176:177]
	s_mov_b32 m0, s68
	ds_read_b128 v[152:155], v251 offset:16384
	ds_read_b128 v[156:159], v251 offset:17408
	ds_read_b128 v[168:171], v251 offset:18432
	ds_read_b128 v[172:175], v251 offset:19456
	ds_read_b128 v[200:203], v251 offset:20480
	ds_read_b128 v[204:207], v251 offset:21504
	ds_read_b128 v[208:211], v251 offset:22528
	ds_read_b128 v[212:215], v251 offset:23552
	global_load_lds_dwordx4 v176, s[0:1]
	s_add_i32 m0, s68, 0x2000
	s_add_u32 s68, s0, 0x40000
	v_lshl_add_u64 v[180:181], s[0:1], 0, v[190:191]
	s_addc_u32 s69, s1, 0
	s_add_i32 s70, s70, s27
	global_load_lds_dwordx4 v190, s[0:1]
	s_mov_b32 m0, s70
	v_lshl_add_u64 v[188:189], s[4:5], 0, v[192:193]
	global_load_lds_dwordx4 v176, s[68:69]
	s_add_i32 m0, s70, 0x2000
	s_nop 0
	global_load_lds_dwordx4 v190, s[68:69]
	v_lshl_add_u64 v[186:187], s[4:5], 0, v[194:195]
	s_mov_b32 m0, s20
	s_nop 0
	global_load_lds_dwordx4 v194, s[4:5]
	s_mov_b32 m0, s12
	s_nop 0
	global_load_lds_dwordx4 v192, s[4:5]
	s_waitcnt vmcnt(8)
	s_waitcnt lgkmcnt(0)
	s_barrier
	s_setprio 1
	s_waitcnt lgkmcnt(0)
	v_mfma_f32_16x16x32_bf16 v[76:79], v[40:43], v[152:155], 0
	v_mfma_f32_16x16x32_bf16 v[72:75], v[56:59], v[152:155], 0
	v_mfma_f32_16x16x32_bf16 v[52:55], v[40:43], v[168:171], 0
	v_mfma_f32_16x16x32_bf16 v[48:51], v[56:59], v[168:171], 0
	v_mfma_f32_16x16x32_bf16 v[28:31], v[40:43], v[200:203], 0
	v_mfma_f32_16x16x32_bf16 v[24:27], v[56:59], v[200:203], 0
	v_mfma_f32_16x16x32_bf16 v[12:15], v[40:43], v[208:211], 0
	v_mfma_f32_16x16x32_bf16 v[8:11], v[56:59], v[208:211], 0
	v_mfma_f32_16x16x32_bf16 v[76:79], v[44:47], v[156:159], v[76:79]
	v_mfma_f32_16x16x32_bf16 v[72:75], v[60:63], v[156:159], v[72:75]
	v_mfma_f32_16x16x32_bf16 v[52:55], v[44:47], v[172:175], v[52:55]
	v_mfma_f32_16x16x32_bf16 v[48:51], v[60:63], v[172:175], v[48:51]
	v_mfma_f32_16x16x32_bf16 v[28:31], v[44:47], v[204:207], v[28:31]
	v_mfma_f32_16x16x32_bf16 v[24:27], v[60:63], v[204:207], v[24:27]
	v_mfma_f32_16x16x32_bf16 v[12:15], v[44:47], v[212:215], v[12:15]
	v_mfma_f32_16x16x32_bf16 v[8:11], v[60:63], v[212:215], v[8:11]
	s_setprio 0
	s_setprio 1
	v_mfma_f32_16x16x32_bf16 v[36:39], v[104:107], v[168:171], 0
	v_mfma_f32_16x16x32_bf16 v[32:35], v[120:123], v[168:171], 0
	v_mfma_f32_16x16x32_bf16 v[20:23], v[104:107], v[200:203], 0
	v_mfma_f32_16x16x32_bf16 v[16:19], v[120:123], v[200:203], 0
	v_mfma_f32_16x16x32_bf16 v[4:7], v[104:107], v[208:211], 0
	v_mfma_f32_16x16x32_bf16 v[0:3], v[120:123], v[208:211], 0
	v_mfma_f32_16x16x32_bf16 v[40:43], v[104:107], v[152:155], 0
	v_mfma_f32_16x16x32_bf16 v[44:47], v[120:123], v[152:155], 0
	v_mfma_f32_16x16x32_bf16 v[36:39], v[112:115], v[172:175], v[36:39]
	v_mfma_f32_16x16x32_bf16 v[32:35], v[124:127], v[172:175], v[32:35]
	v_mfma_f32_16x16x32_bf16 v[20:23], v[112:115], v[204:207], v[20:23]
	v_mfma_f32_16x16x32_bf16 v[16:19], v[124:127], v[204:207], v[16:19]
	v_mfma_f32_16x16x32_bf16 v[4:7], v[112:115], v[212:215], v[4:7]
	v_mfma_f32_16x16x32_bf16 v[0:3], v[124:127], v[212:215], v[0:3]
	v_mfma_f32_16x16x32_bf16 v[40:43], v[112:115], v[156:159], v[40:43]
	v_mfma_f32_16x16x32_bf16 v[44:47], v[124:127], v[156:159], v[44:47]
	s_setprio 0
	s_barrier
	s_add_i32 s68, 0, 0x18000
	s_add_i32 s69, 0, 0x1c000
	v_add_u32_e32 v68, s68, v250
	v_add_u32_e32 v124, s69, v250
	ds_read_b128 v[56:59], v68
	ds_read_b128 v[60:63], v68 offset:1024
	ds_read_b128 v[64:67], v68 offset:2048
	ds_read_b128 v[68:71], v68 offset:3072
	ds_read_b128 v[104:107], v124
	ds_read_b128 v[112:115], v124 offset:1024
	ds_read_b128 v[120:123], v124 offset:2048
	ds_read_b128 v[124:127], v124 offset:3072
	s_add_u32 s4, s4, 0x40000
	s_addc_u32 s5, s5, 0
	s_mov_b32 m0, s60
	ds_read_b128 v[152:155], v251 offset:32768
	ds_read_b128 v[156:159], v251 offset:33792
	ds_read_b128 v[168:171], v251 offset:34816
	ds_read_b128 v[172:175], v251 offset:35840
	ds_read_b128 v[200:203], v251 offset:36864
	ds_read_b128 v[204:207], v251 offset:37888
	ds_read_b128 v[208:211], v251 offset:38912
	ds_read_b128 v[212:215], v251 offset:39936
	global_load_lds_dwordx4 v194, s[4:5]
	s_mov_b32 m0, s61
	s_nop 0
	global_load_lds_dwordx4 v192, s[4:5]
	s_waitcnt vmcnt(8)
	s_waitcnt lgkmcnt(0)
	s_barrier
	s_setprio 1
	s_waitcnt lgkmcnt(0)
	v_mfma_f32_16x16x32_bf16 v[164:167], v[56:59], v[152:155], v[164:167]
	v_mfma_f32_16x16x32_bf16 v[160:163], v[64:67], v[152:155], v[160:163]
	v_mfma_f32_16x16x32_bf16 v[116:119], v[56:59], v[168:171], v[116:119]
	v_mfma_f32_16x16x32_bf16 v[108:111], v[64:67], v[168:171], v[108:111]
	v_mfma_f32_16x16x32_bf16 v[140:143], v[56:59], v[200:203], v[140:143]
	v_mfma_f32_16x16x32_bf16 v[136:139], v[64:67], v[200:203], v[136:139]
	v_mfma_f32_16x16x32_bf16 v[92:95], v[56:59], v[208:211], v[92:95]
	v_mfma_f32_16x16x32_bf16 v[88:91], v[64:67], v[208:211], v[88:91]
	v_mfma_f32_16x16x32_bf16 v[164:167], v[60:63], v[156:159], v[164:167]
	v_mfma_f32_16x16x32_bf16 v[160:163], v[68:71], v[156:159], v[160:163]
	v_mfma_f32_16x16x32_bf16 v[116:119], v[60:63], v[172:175], v[116:119]
	v_mfma_f32_16x16x32_bf16 v[108:111], v[68:71], v[172:175], v[108:111]
	v_mfma_f32_16x16x32_bf16 v[140:143], v[60:63], v[204:207], v[140:143]
	v_mfma_f32_16x16x32_bf16 v[136:139], v[68:71], v[204:207], v[136:139]
	v_mfma_f32_16x16x32_bf16 v[92:95], v[60:63], v[212:215], v[92:95]
	v_mfma_f32_16x16x32_bf16 v[88:91], v[68:71], v[212:215], v[88:91]
	s_setprio 0
	s_setprio 1
	v_mfma_f32_16x16x32_bf16 v[148:151], v[104:107], v[152:155], v[148:151]
	v_mfma_f32_16x16x32_bf16 v[144:147], v[120:123], v[152:155], v[144:147]
	v_mfma_f32_16x16x32_bf16 v[100:103], v[104:107], v[168:171], v[100:103]
	v_mfma_f32_16x16x32_bf16 v[96:99], v[120:123], v[168:171], v[96:99]
	v_mfma_f32_16x16x32_bf16 v[132:135], v[104:107], v[200:203], v[132:135]
	v_mfma_f32_16x16x32_bf16 v[128:131], v[120:123], v[200:203], v[128:131]
	v_mfma_f32_16x16x32_bf16 v[84:87], v[104:107], v[208:211], v[84:87]
	v_mfma_f32_16x16x32_bf16 v[80:83], v[120:123], v[208:211], v[80:83]
	v_mfma_f32_16x16x32_bf16 v[148:151], v[112:115], v[156:159], v[148:151]
	v_mfma_f32_16x16x32_bf16 v[144:147], v[124:127], v[156:159], v[144:147]
	v_mfma_f32_16x16x32_bf16 v[100:103], v[112:115], v[172:175], v[100:103]
	v_mfma_f32_16x16x32_bf16 v[96:99], v[124:127], v[172:175], v[96:99]
	v_mfma_f32_16x16x32_bf16 v[132:135], v[112:115], v[204:207], v[132:135]
	v_mfma_f32_16x16x32_bf16 v[128:131], v[124:127], v[204:207], v[128:131]
	v_mfma_f32_16x16x32_bf16 v[84:87], v[112:115], v[212:215], v[84:87]
	v_mfma_f32_16x16x32_bf16 v[80:83], v[124:127], v[212:215], v[80:83]
	s_setprio 0
	s_barrier
	s_add_i32 s4, s68, s27
	v_lshl_add_u64 v[178:179], v[178:179], 0, s[82:83]
	s_mov_b32 m0, s4
	ds_read_b128 v[152:155], v251 offset:49152
	ds_read_b128 v[156:159], v251 offset:50176
	ds_read_b128 v[168:171], v251 offset:51200
	ds_read_b128 v[172:175], v251 offset:52224
	ds_read_b128 v[200:203], v251 offset:53248
	ds_read_b128 v[204:207], v251 offset:54272
	ds_read_b128 v[208:211], v251 offset:55296
	ds_read_b128 v[212:215], v251 offset:56320
	global_load_lds_dwordx4 v[178:179], off
	s_add_i32 m0, s4, 0x2000
	s_add_u32 s0, s0, 0x40080
	v_lshl_add_u64 v[178:179], v[180:181], 0, s[82:83]
	s_addc_u32 s1, s1, 0
	s_add_i32 s4, s69, s27
	global_load_lds_dwordx4 v[178:179], off
	s_mov_b32 m0, s4
	s_nop 0
	global_load_lds_dwordx4 v176, s[0:1]
	s_add_i32 m0, s4, 0x2000
	s_nop 0
	global_load_lds_dwordx4 v190, s[0:1]
	v_lshl_add_u64 v[178:179], v[186:187], 0, s[82:83]
	s_mov_b32 m0, s64
	s_nop 0
	global_load_lds_dwordx4 v[178:179], off
	v_lshl_add_u64 v[178:179], v[188:189], 0, s[82:83]
	s_mov_b32 m0, s65
	s_nop 0
	global_load_lds_dwordx4 v[178:179], off
	s_waitcnt vmcnt(8)
	s_waitcnt lgkmcnt(0)
	s_barrier
	s_setprio 1
	s_waitcnt lgkmcnt(0)
	v_mfma_f32_16x16x32_bf16 v[76:79], v[56:59], v[152:155], v[76:79]
	v_mfma_f32_16x16x32_bf16 v[72:75], v[64:67], v[152:155], v[72:75]
	v_mfma_f32_16x16x32_bf16 v[52:55], v[56:59], v[168:171], v[52:55]
	v_mfma_f32_16x16x32_bf16 v[48:51], v[64:67], v[168:171], v[48:51]
	v_mfma_f32_16x16x32_bf16 v[28:31], v[56:59], v[200:203], v[28:31]
	v_mfma_f32_16x16x32_bf16 v[24:27], v[64:67], v[200:203], v[24:27]
	v_mfma_f32_16x16x32_bf16 v[12:15], v[56:59], v[208:211], v[12:15]
	v_mfma_f32_16x16x32_bf16 v[8:11], v[64:67], v[208:211], v[8:11]
	v_mfma_f32_16x16x32_bf16 v[76:79], v[60:63], v[156:159], v[76:79]
	v_mfma_f32_16x16x32_bf16 v[72:75], v[68:71], v[156:159], v[72:75]
	v_mfma_f32_16x16x32_bf16 v[52:55], v[60:63], v[172:175], v[52:55]
	v_mfma_f32_16x16x32_bf16 v[48:51], v[68:71], v[172:175], v[48:51]
	v_mfma_f32_16x16x32_bf16 v[28:31], v[60:63], v[204:207], v[28:31]
	v_mfma_f32_16x16x32_bf16 v[24:27], v[68:71], v[204:207], v[24:27]
	v_mfma_f32_16x16x32_bf16 v[12:15], v[60:63], v[212:215], v[12:15]
	v_mfma_f32_16x16x32_bf16 v[8:11], v[68:71], v[212:215], v[8:11]
	s_setprio 0
	s_setprio 1
	v_mfma_f32_16x16x32_bf16 v[40:43], v[104:107], v[152:155], v[40:43]
	v_mfma_f32_16x16x32_bf16 v[68:71], v[112:115], v[156:159], v[40:43]
	v_mfma_f32_16x16x32_bf16 v[40:43], v[120:123], v[152:155], v[44:47]
	v_mfma_f32_16x16x32_bf16 v[36:39], v[104:107], v[168:171], v[36:39]
	v_mfma_f32_16x16x32_bf16 v[32:35], v[120:123], v[168:171], v[32:35]
	v_mfma_f32_16x16x32_bf16 v[20:23], v[104:107], v[200:203], v[20:23]
	v_mfma_f32_16x16x32_bf16 v[16:19], v[120:123], v[200:203], v[16:19]
	v_mfma_f32_16x16x32_bf16 v[4:7], v[104:107], v[208:211], v[4:7]
	v_mfma_f32_16x16x32_bf16 v[0:3], v[120:123], v[208:211], v[0:3]
	v_mfma_f32_16x16x32_bf16 v[64:67], v[124:127], v[156:159], v[40:43]
	v_mfma_f32_16x16x32_bf16 v[36:39], v[112:115], v[172:175], v[36:39]
	v_mfma_f32_16x16x32_bf16 v[32:35], v[124:127], v[172:175], v[32:35]
	v_mfma_f32_16x16x32_bf16 v[20:23], v[112:115], v[204:207], v[20:23]
	v_mfma_f32_16x16x32_bf16 v[16:19], v[124:127], v[204:207], v[16:19]
	v_mfma_f32_16x16x32_bf16 v[4:7], v[112:115], v[212:215], v[4:7]
	v_mfma_f32_16x16x32_bf16 v[0:3], v[124:127], v[212:215], v[0:3]
	s_setprio 0
	s_barrier
	s_add_i32 s47, s47, 2
	s_add_u32 s40, s40, 0x100
	s_addc_u32 s41, s41, 0
	s_add_u32 s43, s43, 0x100
	s_addc_u32 s46, s46, 0
	s_cmp_gt_u32 s47, 13

.Lpeel_748:
	s_add_u32 s0, s44, 0xfffc0080
	s_addc_u32 s1, s45, -1
	s_add_i32 s74, 0, 0x10000
	s_cmp_eq_u32 s73, 12
	s_cselect_b32 s5, s6, s1
	s_cselect_b32 s4, s7, s0
	s_cselect_b32 s1, s39, s72
	s_cselect_b32 s0, s41, s49
	s_add_i32 s92, 0, 0x14000
	v_add_u32_e32 v124, s74, v199
	v_add_u32_e32 v140, s92, v199
	ds_read_b128 v[112:115], v124
	ds_read_b128 v[116:119], v124 offset:1024
	ds_read_b128 v[120:123], v124 offset:2048
	ds_read_b128 v[124:127], v124 offset:3072
	ds_read_b128 v[128:131], v140
	ds_read_b128 v[132:135], v140 offset:1024
	ds_read_b128 v[136:139], v140 offset:2048
	ds_read_b128 v[140:143], v140 offset:3072
	s_add_i32 m0, s63, 0xc000
	ds_read_b128 v[172:175], v207
	ds_read_b128 v[178:181], v207 offset:1024
	ds_read_b128 v[186:189], v207 offset:2048
	ds_read_b128 v[190:193], v207 offset:3072
	ds_read_b128 v[194:197], v207 offset:4096
	ds_read_b128 v[200:203], v207 offset:5120
	ds_read_b128 v[208:211], v207 offset:6144
	ds_read_b128 v[212:215], v207 offset:7168
	global_load_lds_dwordx4 v168, s[44:45]
	s_add_i32 m0, s63, 0xe000
	s_nop 0
	global_load_lds_dwordx4 v170, s[44:45]
	s_waitcnt vmcnt(8)
	s_waitcnt lgkmcnt(0)
	s_barrier
	s_setprio 1
	s_waitcnt lgkmcnt(0)
	v_mfma_f32_16x16x32_bf16 v[156:159], v[112:115], v[172:175], 0
	v_mfma_f32_16x16x32_bf16 v[152:155], v[120:123], v[172:175], 0
	v_mfma_f32_16x16x32_bf16 v[108:111], v[112:115], v[186:189], 0
	v_mfma_f32_16x16x32_bf16 v[100:103], v[120:123], v[186:189], 0
	v_mfma_f32_16x16x32_bf16 v[92:95], v[112:115], v[194:197], 0
	v_mfma_f32_16x16x32_bf16 v[84:87], v[120:123], v[194:197], 0
	v_mfma_f32_16x16x32_bf16 v[76:79], v[112:115], v[208:211], 0
	v_mfma_f32_16x16x32_bf16 v[68:71], v[120:123], v[208:211], 0
	v_mfma_f32_16x16x32_bf16 v[156:159], v[116:119], v[178:181], v[156:159]
	v_mfma_f32_16x16x32_bf16 v[152:155], v[124:127], v[178:181], v[152:155]
	v_mfma_f32_16x16x32_bf16 v[108:111], v[116:119], v[190:193], v[108:111]
	v_mfma_f32_16x16x32_bf16 v[100:103], v[124:127], v[190:193], v[100:103]
	v_mfma_f32_16x16x32_bf16 v[92:95], v[116:119], v[200:203], v[92:95]
	v_mfma_f32_16x16x32_bf16 v[84:87], v[124:127], v[200:203], v[84:87]
	v_mfma_f32_16x16x32_bf16 v[76:79], v[116:119], v[212:215], v[76:79]
	v_mfma_f32_16x16x32_bf16 v[68:71], v[124:127], v[212:215], v[68:71]
	s_setprio 0
	s_setprio 1
	v_mfma_f32_16x16x32_bf16 v[148:151], v[128:131], v[172:175], 0
	v_mfma_f32_16x16x32_bf16 v[144:147], v[136:139], v[172:175], 0
	v_mfma_f32_16x16x32_bf16 v[104:107], v[128:131], v[186:189], 0
	v_mfma_f32_16x16x32_bf16 v[96:99], v[136:139], v[186:189], 0
	v_mfma_f32_16x16x32_bf16 v[88:91], v[128:131], v[194:197], 0
	v_mfma_f32_16x16x32_bf16 v[80:83], v[136:139], v[194:197], 0
	v_mfma_f32_16x16x32_bf16 v[72:75], v[128:131], v[208:211], 0
	v_mfma_f32_16x16x32_bf16 v[64:67], v[136:139], v[208:211], 0
	v_mfma_f32_16x16x32_bf16 v[148:151], v[132:135], v[178:181], v[148:151]
	v_mfma_f32_16x16x32_bf16 v[144:147], v[140:143], v[178:181], v[144:147]
	v_mfma_f32_16x16x32_bf16 v[104:107], v[132:135], v[190:193], v[104:107]
	v_mfma_f32_16x16x32_bf16 v[96:99], v[140:143], v[190:193], v[96:99]
	v_mfma_f32_16x16x32_bf16 v[88:91], v[132:135], v[200:203], v[88:91]
	v_mfma_f32_16x16x32_bf16 v[80:83], v[140:143], v[200:203], v[80:83]
	v_mfma_f32_16x16x32_bf16 v[72:75], v[132:135], v[212:215], v[72:75]
	v_mfma_f32_16x16x32_bf16 v[64:67], v[140:143], v[212:215], v[64:67]
	s_setprio 0
	s_barrier
	s_add_i32 s74, s74, s62
	v_lshl_add_u64 v[182:183], s[0:1], 0, v[164:165]
	s_mov_b32 m0, s74
	ds_read_b128 v[172:175], v207 offset:16384
	ds_read_b128 v[178:181], v207 offset:17408
	ds_read_b128 v[186:189], v207 offset:18432
	ds_read_b128 v[190:193], v207 offset:19456
	ds_read_b128 v[194:197], v207 offset:20480
	ds_read_b128 v[200:203], v207 offset:21504
	ds_read_b128 v[208:211], v207 offset:22528
	ds_read_b128 v[212:215], v207 offset:23552
	global_load_lds_dwordx4 v164, s[0:1]
	s_add_i32 m0, s74, 0x2000
	s_add_u32 s74, s0, 0x40000
	v_lshl_add_u64 v[204:205], s[0:1], 0, v[160:161]
	s_addc_u32 s75, s1, 0
	s_add_i32 s92, s92, s62
	global_load_lds_dwordx4 v160, s[0:1]
	s_mov_b32 m0, s92
	v_lshl_add_u64 v[218:219], s[4:5], 0, v[162:163]
	global_load_lds_dwordx4 v164, s[74:75]
	s_add_i32 m0, s92, 0x2000
	s_nop 0
	global_load_lds_dwordx4 v160, s[74:75]
	v_lshl_add_u64 v[216:217], s[4:5], 0, v[166:167]
	s_mov_b32 m0, s63
	s_nop 0
	global_load_lds_dwordx4 v166, s[4:5]
	s_mov_b32 m0, s64
	s_nop 0
	global_load_lds_dwordx4 v162, s[4:5]
	s_waitcnt vmcnt(8)
	s_waitcnt lgkmcnt(0)
	s_barrier
	s_setprio 1
	s_waitcnt lgkmcnt(0)
	v_mfma_f32_16x16x32_bf16 v[60:63], v[112:115], v[172:175], 0
	v_mfma_f32_16x16x32_bf16 v[56:59], v[120:123], v[172:175], 0
	v_mfma_f32_16x16x32_bf16 v[44:47], v[112:115], v[186:189], 0
	v_mfma_f32_16x16x32_bf16 v[36:39], v[120:123], v[186:189], 0
	v_mfma_f32_16x16x32_bf16 v[28:31], v[112:115], v[194:197], 0
	v_mfma_f32_16x16x32_bf16 v[20:23], v[120:123], v[194:197], 0
	v_mfma_f32_16x16x32_bf16 v[12:15], v[112:115], v[208:211], 0
	v_mfma_f32_16x16x32_bf16 v[4:7], v[120:123], v[208:211], 0
	v_mfma_f32_16x16x32_bf16 v[60:63], v[116:119], v[178:181], v[60:63]
	v_mfma_f32_16x16x32_bf16 v[56:59], v[124:127], v[178:181], v[56:59]
	v_mfma_f32_16x16x32_bf16 v[44:47], v[116:119], v[190:193], v[44:47]
	v_mfma_f32_16x16x32_bf16 v[36:39], v[124:127], v[190:193], v[36:39]
	v_mfma_f32_16x16x32_bf16 v[28:31], v[116:119], v[200:203], v[28:31]
	v_mfma_f32_16x16x32_bf16 v[20:23], v[124:127], v[200:203], v[20:23]
	v_mfma_f32_16x16x32_bf16 v[12:15], v[116:119], v[212:215], v[12:15]
	v_mfma_f32_16x16x32_bf16 v[4:7], v[124:127], v[212:215], v[4:7]
	s_setprio 0
	s_setprio 1
	v_mfma_f32_16x16x32_bf16 v[52:55], v[128:131], v[172:175], 0
	v_mfma_f32_16x16x32_bf16 v[48:51], v[136:139], v[172:175], 0
	v_mfma_f32_16x16x32_bf16 v[40:43], v[128:131], v[186:189], 0
	v_mfma_f32_16x16x32_bf16 v[32:35], v[136:139], v[186:189], 0
	v_mfma_f32_16x16x32_bf16 v[24:27], v[128:131], v[194:197], 0
	v_mfma_f32_16x16x32_bf16 v[16:19], v[136:139], v[194:197], 0
	v_mfma_f32_16x16x32_bf16 v[8:11], v[128:131], v[208:211], 0
	v_mfma_f32_16x16x32_bf16 v[0:3], v[136:139], v[208:211], 0
	v_mfma_f32_16x16x32_bf16 v[52:55], v[132:135], v[178:181], v[52:55]
	v_mfma_f32_16x16x32_bf16 v[48:51], v[140:143], v[178:181], v[48:51]
	v_mfma_f32_16x16x32_bf16 v[40:43], v[132:135], v[190:193], v[40:43]
	v_mfma_f32_16x16x32_bf16 v[32:35], v[140:143], v[190:193], v[32:35]
	v_mfma_f32_16x16x32_bf16 v[24:27], v[132:135], v[200:203], v[24:27]
	v_mfma_f32_16x16x32_bf16 v[16:19], v[140:143], v[200:203], v[16:19]
	v_mfma_f32_16x16x32_bf16 v[8:11], v[132:135], v[212:215], v[8:11]
	v_mfma_f32_16x16x32_bf16 v[0:3], v[140:143], v[212:215], v[0:3]
	s_setprio 0
	s_barrier
	s_add_i32 s74, 0, 0x18000
	s_add_i32 s75, 0, 0x1c000
	v_add_u32_e32 v124, s74, v199
	v_add_u32_e32 v140, s75, v199
	ds_read_b128 v[112:115], v124
	ds_read_b128 v[116:119], v124 offset:1024
	ds_read_b128 v[120:123], v124 offset:2048
	ds_read_b128 v[124:127], v124 offset:3072
	ds_read_b128 v[128:131], v140
	ds_read_b128 v[132:135], v140 offset:1024
	ds_read_b128 v[136:139], v140 offset:2048
	ds_read_b128 v[140:143], v140 offset:3072
	s_add_u32 s4, s4, 0x40000
	s_addc_u32 s5, s5, 0
	s_mov_b32 m0, s65
	ds_read_b128 v[172:175], v207 offset:32768
	ds_read_b128 v[178:181], v207 offset:33792
	ds_read_b128 v[186:189], v207 offset:34816
	ds_read_b128 v[190:193], v207 offset:35840
	ds_read_b128 v[194:197], v207 offset:36864
	ds_read_b128 v[200:203], v207 offset:37888
	ds_read_b128 v[208:211], v207 offset:38912
	ds_read_b128 v[212:215], v207 offset:39936
	global_load_lds_dwordx4 v166, s[4:5]
	s_mov_b32 m0, s66
	s_nop 0
	global_load_lds_dwordx4 v162, s[4:5]
	s_waitcnt vmcnt(8)
	s_waitcnt lgkmcnt(0)
	s_barrier
	s_setprio 1
	s_waitcnt lgkmcnt(0)
	v_mfma_f32_16x16x32_bf16 v[156:159], v[112:115], v[172:175], v[156:159]
	v_mfma_f32_16x16x32_bf16 v[152:155], v[120:123], v[172:175], v[152:155]
	v_mfma_f32_16x16x32_bf16 v[108:111], v[112:115], v[186:189], v[108:111]
	v_mfma_f32_16x16x32_bf16 v[100:103], v[120:123], v[186:189], v[100:103]
	v_mfma_f32_16x16x32_bf16 v[92:95], v[112:115], v[194:197], v[92:95]
	v_mfma_f32_16x16x32_bf16 v[84:87], v[120:123], v[194:197], v[84:87]
	v_mfma_f32_16x16x32_bf16 v[76:79], v[112:115], v[208:211], v[76:79]
	v_mfma_f32_16x16x32_bf16 v[68:71], v[120:123], v[208:211], v[68:71]
	v_mfma_f32_16x16x32_bf16 v[156:159], v[116:119], v[178:181], v[156:159]
	v_mfma_f32_16x16x32_bf16 v[152:155], v[124:127], v[178:181], v[152:155]
	v_mfma_f32_16x16x32_bf16 v[108:111], v[116:119], v[190:193], v[108:111]
	v_mfma_f32_16x16x32_bf16 v[100:103], v[124:127], v[190:193], v[100:103]
	v_mfma_f32_16x16x32_bf16 v[92:95], v[116:119], v[200:203], v[92:95]
	v_mfma_f32_16x16x32_bf16 v[84:87], v[124:127], v[200:203], v[84:87]
	v_mfma_f32_16x16x32_bf16 v[76:79], v[116:119], v[212:215], v[76:79]
	v_mfma_f32_16x16x32_bf16 v[68:71], v[124:127], v[212:215], v[68:71]
	s_setprio 0
	s_setprio 1
	v_mfma_f32_16x16x32_bf16 v[148:151], v[128:131], v[172:175], v[148:151]
	v_mfma_f32_16x16x32_bf16 v[144:147], v[136:139], v[172:175], v[144:147]
	v_mfma_f32_16x16x32_bf16 v[104:107], v[128:131], v[186:189], v[104:107]
	v_mfma_f32_16x16x32_bf16 v[96:99], v[136:139], v[186:189], v[96:99]
	v_mfma_f32_16x16x32_bf16 v[88:91], v[128:131], v[194:197], v[88:91]
	v_mfma_f32_16x16x32_bf16 v[80:83], v[136:139], v[194:197], v[80:83]
	v_mfma_f32_16x16x32_bf16 v[72:75], v[128:131], v[208:211], v[72:75]
	v_mfma_f32_16x16x32_bf16 v[64:67], v[136:139], v[208:211], v[64:67]
	v_mfma_f32_16x16x32_bf16 v[148:151], v[132:135], v[178:181], v[148:151]
	v_mfma_f32_16x16x32_bf16 v[144:147], v[140:143], v[178:181], v[144:147]
	v_mfma_f32_16x16x32_bf16 v[104:107], v[132:135], v[190:193], v[104:107]
	v_mfma_f32_16x16x32_bf16 v[96:99], v[140:143], v[190:193], v[96:99]
	v_mfma_f32_16x16x32_bf16 v[88:91], v[132:135], v[200:203], v[88:91]
	v_mfma_f32_16x16x32_bf16 v[80:83], v[140:143], v[200:203], v[80:83]
	v_mfma_f32_16x16x32_bf16 v[72:75], v[132:135], v[212:215], v[72:75]
	v_mfma_f32_16x16x32_bf16 v[64:67], v[140:143], v[212:215], v[64:67]
	s_setprio 0
	s_barrier
	s_add_i32 s4, s74, s62
	v_lshl_add_u64 v[182:183], v[182:183], 0, s[82:83]
	s_mov_b32 m0, s4
	ds_read_b128 v[172:175], v207 offset:49152
	ds_read_b128 v[178:181], v207 offset:50176
	ds_read_b128 v[186:189], v207 offset:51200
	ds_read_b128 v[190:193], v207 offset:52224
	ds_read_b128 v[194:197], v207 offset:53248
	ds_read_b128 v[200:203], v207 offset:54272
	ds_read_b128 v[208:211], v207 offset:55296
	ds_read_b128 v[212:215], v207 offset:56320
	global_load_lds_dwordx4 v[182:183], off
	s_add_i32 m0, s4, 0x2000
	s_add_u32 s0, s0, 0x40080
	v_lshl_add_u64 v[182:183], v[204:205], 0, s[82:83]
	s_addc_u32 s1, s1, 0
	s_add_i32 s4, s75, s62
	global_load_lds_dwordx4 v[182:183], off
	s_mov_b32 m0, s4
	s_nop 0
	global_load_lds_dwordx4 v164, s[0:1]
	s_add_i32 m0, s4, 0x2000
	s_nop 0
	global_load_lds_dwordx4 v160, s[0:1]
	v_lshl_add_u64 v[182:183], v[216:217], 0, s[82:83]
	s_mov_b32 m0, s69
	s_nop 0
	global_load_lds_dwordx4 v[182:183], off
	v_lshl_add_u64 v[182:183], v[218:219], 0, s[82:83]
	s_mov_b32 m0, s70
	s_nop 0
	global_load_lds_dwordx4 v[182:183], off
	s_waitcnt vmcnt(8)
	s_waitcnt lgkmcnt(0)
	s_barrier
	s_setprio 1
	s_waitcnt lgkmcnt(0)
	v_mfma_f32_16x16x32_bf16 v[60:63], v[112:115], v[172:175], v[60:63]
	v_mfma_f32_16x16x32_bf16 v[56:59], v[120:123], v[172:175], v[56:59]
	v_mfma_f32_16x16x32_bf16 v[44:47], v[112:115], v[186:189], v[44:47]
	v_mfma_f32_16x16x32_bf16 v[36:39], v[120:123], v[186:189], v[36:39]
	v_mfma_f32_16x16x32_bf16 v[28:31], v[112:115], v[194:197], v[28:31]
	v_mfma_f32_16x16x32_bf16 v[20:23], v[120:123], v[194:197], v[20:23]
	v_mfma_f32_16x16x32_bf16 v[12:15], v[112:115], v[208:211], v[12:15]
	v_mfma_f32_16x16x32_bf16 v[4:7], v[120:123], v[208:211], v[4:7]
	v_mfma_f32_16x16x32_bf16 v[60:63], v[116:119], v[178:181], v[60:63]
	v_mfma_f32_16x16x32_bf16 v[56:59], v[124:127], v[178:181], v[56:59]
	v_mfma_f32_16x16x32_bf16 v[44:47], v[116:119], v[190:193], v[44:47]
	v_mfma_f32_16x16x32_bf16 v[36:39], v[124:127], v[190:193], v[36:39]
	v_mfma_f32_16x16x32_bf16 v[28:31], v[116:119], v[200:203], v[28:31]
	v_mfma_f32_16x16x32_bf16 v[20:23], v[124:127], v[200:203], v[20:23]
	v_mfma_f32_16x16x32_bf16 v[12:15], v[116:119], v[212:215], v[12:15]
	v_mfma_f32_16x16x32_bf16 v[4:7], v[124:127], v[212:215], v[4:7]
	s_setprio 0
	s_setprio 1
	v_mfma_f32_16x16x32_bf16 v[52:55], v[128:131], v[172:175], v[52:55]
	v_mfma_f32_16x16x32_bf16 v[48:51], v[136:139], v[172:175], v[48:51]
	v_mfma_f32_16x16x32_bf16 v[40:43], v[128:131], v[186:189], v[40:43]
	v_mfma_f32_16x16x32_bf16 v[32:35], v[136:139], v[186:189], v[32:35]
	v_mfma_f32_16x16x32_bf16 v[24:27], v[128:131], v[194:197], v[24:27]
	v_mfma_f32_16x16x32_bf16 v[16:19], v[136:139], v[194:197], v[16:19]
	v_mfma_f32_16x16x32_bf16 v[8:11], v[128:131], v[208:211], v[8:11]
	v_mfma_f32_16x16x32_bf16 v[0:3], v[136:139], v[208:211], v[0:3]
	v_mfma_f32_16x16x32_bf16 v[52:55], v[132:135], v[178:181], v[52:55]
	v_mfma_f32_16x16x32_bf16 v[48:51], v[140:143], v[178:181], v[48:51]
	v_mfma_f32_16x16x32_bf16 v[40:43], v[132:135], v[190:193], v[40:43]
	v_mfma_f32_16x16x32_bf16 v[32:35], v[140:143], v[190:193], v[32:35]
	v_mfma_f32_16x16x32_bf16 v[24:27], v[132:135], v[200:203], v[24:27]
	v_mfma_f32_16x16x32_bf16 v[16:19], v[140:143], v[200:203], v[16:19]
	v_mfma_f32_16x16x32_bf16 v[8:11], v[132:135], v[212:215], v[8:11]
	v_mfma_f32_16x16x32_bf16 v[0:3], v[140:143], v[212:215], v[0:3]
	s_setprio 0
	s_barrier
	s_add_i32 s73, s73, 2
	s_add_u32 s44, s44, 0x100
	s_addc_u32 s45, s45, 0
	s_add_u32 s49, s49, 0x100
	s_addc_u32 s72, s72, 0
	s_cmp_gt_u32 s73, 13
